# static-prio1-waves0-3-no-toggles
# speedup vs baseline: 1.0053x; 1.0053x over previous
; #define LAS __attribute__((address_space(3)))
; __device__ __forceinline__ KArgs kargs() { KArgs p = (KArgs)__builtin_amdgcn_kernarg_segment_ptr(); asm volatile("" : "+s"(p)); return p; }
; __global__ void __launch_bounds__(512, 2) fwd_megakernel(Args a_kernarg) {
;     extern __shared__ __attribute__((aligned(16))) unsigned char lds_raw[];
;     cg::grid_group grid = cg::this_grid();
;     ...
;     { volatile LAS unsigned* st0 = (volatile LAS unsigned*)((LAS unsigned char*)lds_raw + LDS_BYTES - 64); if (threadIdx.x < 2) st0[threadIdx.x] = 0u; }
;     __syncthreads();
;     const XcdBarrier xbar = xcd_barrier_post((unsigned*)(kargs()->ws), (volatile LAS unsigned*)((LAS unsigned char*)lds_raw + LDS_BYTES - 64));
_Z14fwd_megakernel4Args:
	s_mov_b64 s[86:87], s[0:1]
	s_load_dwordx2 s[84:85], s[0:1], 0xa8
	s_nop 0
	s_load_dword s0, s[0:1], 0xb0
	v_and_b32_e32 v186, 0x3ff, v0
	s_mov_b32 s82, s2
	v_cmp_gt_u32_e32 vcc, 2, v186
	s_waitcnt lgkmcnt(0)
	v_writelane_b32 v254, s0, 0
	s_add_u32 s0, s86, 0xa8
	s_addc_u32 s1, s87, 0
	s_and_saveexec_b64 s[2:3], vcc
	v_lshl_add_u32 v1, v186, 2, 0
	v_add_u32_e32 v1, 0x23fc0, v1
	v_mov_b32_e32 v2, 0
	ds_write_b32 v1, v2
	s_or_b64 exec, exec, s[2:3]
	v_readfirstlane_b32 s98, v186
	s_cmpk_lt_u32 s98, 0x100
	s_cbranch_scc0 .Lprio_lo
	s_setprio 1
